# x069 + ssd1 MFMA loop: the 4 B fragments of a k-slab read into distinct quads ahead of the scaling VALU (no per-pair LDS wait)
# speedup vs baseline: 1.0024x; 1.0024x over previous
.LBB0_170:
	v_add_u32_e32 v200, 32, v0
	v_add_u32_e32 v190, 0x19800, v200
	v_add_u32_e32 v202, 32, v188
	ds_read_b128 v[134:137], v202
	ds_read_b128 v[130:133], v202 offset:32
	ds_read_b128 v[138:141], v202 offset:8704
	ds_read_b128 v[190:193], v190
	v_add_u32_e32 v239, 0x11020, v189
	ds_read_b128 v[204:207], v239
	v_add_u32_e32 v239, 0x13220, v189
	ds_read_b128 v[208:211], v239
	v_add_u32_e32 v239, 0x15420, v189
	ds_read_b128 v[212:215], v239
	v_add_u32_e32 v239, 0x17620, v189
	ds_read_b128 v[244:247], v239
	v_add_u32_e32 v201, 0x19810, v200
	s_waitcnt lgkmcnt(7)
	v_lshlrev_b32_e32 v194, 16, v134
	v_and_b32_e32 v195, 0xffff0000, v134
	s_add_i32 s6, s6, -2
	s_waitcnt lgkmcnt(4)
	v_pk_mul_f32 v[194:195], v[190:191], v[194:195]
	v_add_u32_e32 v188, 64, v188
	v_cvt_pk_bf16_f32 v134, v194, v195
	v_lshlrev_b32_e32 v194, 16, v138
	v_and_b32_e32 v195, 0xffff0000, v138
	v_pk_mul_f32 v[190:191], v[190:191], v[194:195]
	v_lshlrev_b32_e32 v194, 16, v136
	v_cvt_pk_bf16_f32 v138, v190, v191
	v_lshlrev_b32_e32 v190, 16, v135
	v_and_b32_e32 v191, 0xffff0000, v135
	v_pk_mul_f32 v[190:191], v[192:193], v[190:191]
	v_and_b32_e32 v195, 0xffff0000, v136
	v_cvt_pk_bf16_f32 v135, v190, v191
	v_lshlrev_b32_e32 v190, 16, v139
	v_and_b32_e32 v191, 0xffff0000, v139
	v_pk_mul_f32 v[190:191], v[192:193], v[190:191]
	v_add_u32_e32 v0, 0x80, v0
	v_cvt_pk_bf16_f32 v139, v190, v191
	ds_read_b128 v[190:193], v201
	s_cmp_eq_u32 s6, 0
	s_waitcnt lgkmcnt(0)
	v_pk_mul_f32 v[194:195], v[190:191], v[194:195]
	s_nop 0
	v_cvt_pk_bf16_f32 v136, v194, v195
	v_lshlrev_b32_e32 v194, 16, v140
	v_and_b32_e32 v195, 0xffff0000, v140
	v_pk_mul_f32 v[190:191], v[190:191], v[194:195]
	s_nop 0
	v_cvt_pk_bf16_f32 v140, v190, v191
	v_lshlrev_b32_e32 v190, 16, v137
	v_and_b32_e32 v191, 0xffff0000, v137
	v_pk_mul_f32 v[190:191], v[192:193], v[190:191]
	s_nop 0
	v_cvt_pk_bf16_f32 v137, v190, v191
	v_lshlrev_b32_e32 v190, 16, v141
	v_and_b32_e32 v191, 0xffff0000, v141
	v_pk_mul_f32 v[190:191], v[192:193], v[190:191]
	s_nop 0
	v_cvt_pk_bf16_f32 v141, v190, v191
	v_add_u32_e32 v190, 32, v189
	v_add_u32_e32 v191, 0x11000, v190
	v_add_u32_e32 v191, 0x13200, v190
	v_mfma_f32_32x32x16_bf16 v[114:129], v[134:137], v[204:207], v[114:129]
	v_add_u32_e32 v189, 64, v189
	v_mfma_f32_32x32x16_bf16 v[50:65], v[138:141], v[204:207], v[50:65]
	v_add_u32_e32 v191, 0x15400, v190
	v_mfma_f32_32x32x16_bf16 v[98:113], v[134:137], v[208:211], v[98:113]
	v_mfma_f32_32x32x16_bf16 v[34:49], v[138:141], v[208:211], v[34:49]
	v_add_u32_e32 v191, 0x17600, v190
	v_mfma_f32_32x32x16_bf16 v[82:97], v[134:137], v[212:215], v[82:97]
	v_mfma_f32_32x32x16_bf16 v[18:33], v[138:141], v[212:215], v[18:33]
	v_add_u32_e32 v191, 0x19850, v200
	v_mfma_f32_32x32x16_bf16 v[2:17], v[138:141], v[244:247], v[2:17]
	v_add_u32_e32 v138, 0x19840, v200
	v_mfma_f32_32x32x16_bf16 v[66:81], v[134:137], v[244:247], v[66:81]
	v_add_u32_e32 v239, 0x11020, v190
	ds_read_b128 v[222:225], v239
	v_add_u32_e32 v239, 0x13220, v190
	ds_read_b128 v[226:229], v239
	v_add_u32_e32 v239, 0x15420, v190
	ds_read_b128 v[230:233], v239
	v_add_u32_e32 v239, 0x17620, v190
	ds_read_b128 v[240:243], v239
	ds_read_b128 v[134:137], v202 offset:8736
	ds_read_b128 v[138:141], v138
	v_lshlrev_b32_e32 v192, 16, v130
	v_and_b32_e32 v193, 0xffff0000, v130
	s_waitcnt lgkmcnt(0)
	v_pk_mul_f32 v[192:193], v[138:139], v[192:193]
	s_nop 0
	v_cvt_pk_bf16_f32 v130, v192, v193
	v_lshlrev_b32_e32 v192, 16, v134
	v_and_b32_e32 v193, 0xffff0000, v134
	v_pk_mul_f32 v[138:139], v[138:139], v[192:193]
	v_lshlrev_b32_e32 v192, 16, v132
	v_cvt_pk_bf16_f32 v134, v138, v139
	v_lshlrev_b32_e32 v138, 16, v131
	v_and_b32_e32 v139, 0xffff0000, v131
	v_pk_mul_f32 v[138:139], v[140:141], v[138:139]
	v_and_b32_e32 v193, 0xffff0000, v132
	v_cvt_pk_bf16_f32 v131, v138, v139
	v_lshlrev_b32_e32 v138, 16, v135
	v_and_b32_e32 v139, 0xffff0000, v135
	v_pk_mul_f32 v[138:139], v[140:141], v[138:139]
	s_nop 0
	v_cvt_pk_bf16_f32 v135, v138, v139
	ds_read_b128 v[138:141], v191
	s_waitcnt lgkmcnt(0)
	v_pk_mul_f32 v[192:193], v[138:139], v[192:193]
	s_nop 0
	v_cvt_pk_bf16_f32 v132, v192, v193
	v_lshlrev_b32_e32 v192, 16, v136
	v_and_b32_e32 v193, 0xffff0000, v136
	v_pk_mul_f32 v[138:139], v[138:139], v[192:193]
	s_nop 0
	v_cvt_pk_bf16_f32 v136, v138, v139
	v_lshlrev_b32_e32 v138, 16, v133
	v_and_b32_e32 v139, 0xffff0000, v133
	v_pk_mul_f32 v[138:139], v[140:141], v[138:139]
	s_nop 0
	v_cvt_pk_bf16_f32 v133, v138, v139
	v_lshlrev_b32_e32 v138, 16, v137
	v_and_b32_e32 v139, 0xffff0000, v137
	v_pk_mul_f32 v[138:139], v[140:141], v[138:139]
	s_nop 0
	v_cvt_pk_bf16_f32 v137, v138, v139
	v_mfma_f32_32x32x16_bf16 v[114:129], v[130:133], v[222:225], v[114:129]
	v_mfma_f32_32x32x16_bf16 v[50:65], v[134:137], v[222:225], v[50:65]
	v_mfma_f32_32x32x16_bf16 v[98:113], v[130:133], v[226:229], v[98:113]
	v_mfma_f32_32x32x16_bf16 v[34:49], v[134:137], v[226:229], v[34:49]
	v_mfma_f32_32x32x16_bf16 v[82:97], v[130:133], v[230:233], v[82:97]
	v_mfma_f32_32x32x16_bf16 v[18:33], v[134:137], v[230:233], v[18:33]
	v_mfma_f32_32x32x16_bf16 v[66:81], v[130:133], v[240:243], v[66:81]
	v_mfma_f32_32x32x16_bf16 v[2:17], v[134:137], v[240:243], v[2:17]
	s_cbranch_scc0 .LBB0_170
	s_movk_i32 s11, 0x80
	s_mov_b64 s[6:7], 0
	s_and_b64 vcc, exec, s[4:5]
	s_cbranch_vccz .LBB0_169
	s_cmp_lg_u32 s0, 0
	s_cbranch_scc0 .LBB0_174
	s_lshl_b32 s1, s9, 6
	s_add_i32 s0, s0, s1
	v_add_u32_e32 v130, s0, v163
	v_ashrrev_i32_e32 v131, 31, v130
	v_readlane_b32 s16, v251, 2
	v_lshlrev_b64 v[130:131], 19, v[130:131]
	v_readlane_b32 s28, v251, 14
	v_readlane_b32 s29, v251, 15
	v_lshlrev_b32_e32 v0, 14, v159
	v_readlane_b32 s17, v251, 3
	v_lshl_add_u64 v[130:131], s[28:29], 0, v[130:131]
	v_readlane_b32 s18, v251, 4
	v_readlane_b32 s19, v251, 5
	v_readlane_b32 s20, v251, 6
	v_readlane_b32 s21, v251, 7
	v_readlane_b32 s22, v251, 8
	v_readlane_b32 s23, v251, 9
	v_readlane_b32 s24, v251, 10
	v_readlane_b32 s25, v251, 11
	v_readlane_b32 s26, v251, 12
	v_readlane_b32 s27, v251, 13
	v_readlane_b32 s30, v251, 16
	v_readlane_b32 s31, v251, 17
	v_lshl_add_u64 v[130:131], v[130:131], 0, v[0:1]
	s_cbranch_execnz .LBB0_165
	s_branch .LBB0_164
